# k5/k12 relu^2 epilogue: canonicalising v_max(x,x) folded into v_max(0,x) (on top of peeled GEMM loops)
# baseline (speedup 1.0000x reference)
.LBB5_12:
	s_lshl_b32 s13, s20, 8
	v_max_f32_e32 v120, 0, v120
	s_add_i32 s22, s13, s39
	v_max_f32_e32 v121, 0, v121
	v_max_f32_e32 v122, 0, v122
	s_ashr_i32 s23, s22, 31
	s_lshl_b32 s24, s53, 8
	v_mul_f32_e32 v152, v120, v120
	v_max_f32_e32 v120, 0, v125
	s_ashr_i32 s25, s24, 31
	s_lshl_b64 s[22:23], s[22:23], 13
	v_max_f32_e32 v124, 0, v124
	v_mul_f32_e32 v125, v121, v121
	v_max_f32_e32 v121, 0, v126
	v_mul_f32_e32 v126, v122, v122
	v_max_f32_e32 v122, 0, v127
	v_max_f32_e32 v123, 0, v123
	s_or_b64 s[24:25], s[24:25], s[6:7]
	v_lshl_add_u64 v[146:147], v[136:137], 0, s[22:23]
	v_mul_f32_e32 v120, v120, v120
	v_max_f32_e32 v112, 0, v112
	v_lshl_add_u64 v[146:147], s[24:25], 1, v[146:147]
	v_mul_f32_e32 v124, v124, v124
	v_mul_f32_e32 v121, v121, v121
	v_mul_f32_e32 v122, v122, v122
	v_mul_f32_e32 v123, v123, v123
	v_cvt_pk_bf16_f32 v120, v124, v120
	v_max_f32_e32 v113, 0, v113
	v_max_f32_e32 v114, 0, v114
	v_cvt_pk_bf16_f32 v121, v121, v122
	v_cvt_pk_bf16_f32 v122, v152, v125
	v_cvt_pk_bf16_f32 v123, v126, v123
	global_store_dwordx4 v[146:147], v[120:123], off
	s_nop 1
	v_mul_f32_e32 v120, v112, v112
	v_max_f32_e32 v112, 0, v117
	v_max_f32_e32 v116, 0, v116
	v_mul_f32_e32 v117, v113, v113
	v_max_f32_e32 v113, 0, v118
	v_mul_f32_e32 v118, v114, v114
	v_max_f32_e32 v114, 0, v119
	v_max_f32_e32 v115, 0, v115
	v_mul_f32_e32 v112, v112, v112
	v_max_f32_e32 v104, 0, v104
	v_mul_f32_e32 v116, v116, v116
	v_mul_f32_e32 v113, v113, v113
	v_mul_f32_e32 v114, v114, v114
	v_mul_f32_e32 v115, v115, v115
	v_cvt_pk_bf16_f32 v112, v116, v112
	v_max_f32_e32 v105, 0, v105
	v_max_f32_e32 v106, 0, v106
	v_cvt_pk_bf16_f32 v113, v113, v114
	v_cvt_pk_bf16_f32 v114, v120, v117
	v_cvt_pk_bf16_f32 v115, v118, v115
	global_store_dwordx4 v[146:147], v[112:115], off offset:256
	s_nop 1
	v_max_f32_e32 v108, 0, v108
	v_mul_f32_e32 v112, v104, v104
	v_max_f32_e32 v104, 0, v109
	v_mul_f32_e32 v109, v105, v105
	v_max_f32_e32 v105, 0, v110
	v_mul_f32_e32 v110, v106, v106
	v_max_f32_e32 v106, 0, v111
	v_mul_f32_e32 v108, v108, v108
	v_mul_f32_e32 v104, v104, v104
	v_max_f32_e32 v107, 0, v107
	v_mul_f32_e32 v105, v105, v105
	v_mul_f32_e32 v106, v106, v106
	v_cvt_pk_bf16_f32 v104, v108, v104
	v_add_co_u32_e32 v108, vcc, s45, v146
	v_max_f32_e32 v96, 0, v96
	v_mul_f32_e32 v107, v107, v107
	v_cvt_pk_bf16_f32 v105, v105, v106
	v_cvt_pk_bf16_f32 v106, v112, v109
	v_addc_co_u32_e32 v109, vcc, 0, v147, vcc
	v_max_f32_e32 v97, 0, v97
	v_max_f32_e32 v98, 0, v98
	v_cvt_pk_bf16_f32 v107, v110, v107
	global_store_dwordx4 v[108:109], v[104:107], off
	s_nop 1
	v_mul_f32_e32 v104, v96, v96
	v_max_f32_e32 v96, 0, v101
	v_max_f32_e32 v100, 0, v100
	v_mul_f32_e32 v101, v97, v97
	v_max_f32_e32 v97, 0, v102
	v_mul_f32_e32 v102, v98, v98
	v_max_f32_e32 v98, 0, v103
	v_max_f32_e32 v99, 0, v99
	v_mul_f32_e32 v96, v96, v96
	v_max_f32_e32 v88, 0, v88
	v_mul_f32_e32 v100, v100, v100
	v_mul_f32_e32 v97, v97, v97
	v_mul_f32_e32 v98, v98, v98
	v_mul_f32_e32 v99, v99, v99
	v_cvt_pk_bf16_f32 v96, v100, v96
	v_max_f32_e32 v89, 0, v89
	v_max_f32_e32 v90, 0, v90
	v_cvt_pk_bf16_f32 v97, v97, v98
	v_cvt_pk_bf16_f32 v98, v104, v101
	v_cvt_pk_bf16_f32 v99, v102, v99
	global_store_dwordx4 v[108:109], v[96:99], off offset:256
	s_nop 1
	v_max_f32_e32 v92, 0, v92
	v_mul_f32_e32 v96, v88, v88
	v_max_f32_e32 v88, 0, v93
	v_mul_f32_e32 v93, v89, v89
	v_max_f32_e32 v89, 0, v94
	v_mul_f32_e32 v94, v90, v90
	v_max_f32_e32 v90, 0, v95
	v_mul_f32_e32 v92, v92, v92
	v_mul_f32_e32 v88, v88, v88
	v_max_f32_e32 v91, 0, v91
	v_mul_f32_e32 v89, v89, v89
	v_mul_f32_e32 v90, v90, v90
	v_cvt_pk_bf16_f32 v88, v92, v88
	v_add_co_u32_e32 v92, vcc, s46, v146
	v_max_f32_e32 v80, 0, v80
	v_mul_f32_e32 v91, v91, v91
	v_cvt_pk_bf16_f32 v89, v89, v90
	v_cvt_pk_bf16_f32 v90, v96, v93
	v_addc_co_u32_e32 v93, vcc, 0, v147, vcc
	v_max_f32_e32 v81, 0, v81
	v_max_f32_e32 v82, 0, v82
	v_cvt_pk_bf16_f32 v91, v94, v91
	global_store_dwordx4 v[92:93], v[88:91], off
	s_nop 1
	v_mul_f32_e32 v88, v80, v80
	v_max_f32_e32 v80, 0, v85
	v_max_f32_e32 v84, 0, v84
	v_mul_f32_e32 v85, v81, v81
	v_max_f32_e32 v81, 0, v86
	v_mul_f32_e32 v86, v82, v82
	v_max_f32_e32 v82, 0, v87
	v_max_f32_e32 v83, 0, v83
	v_mul_f32_e32 v80, v80, v80
	v_max_f32_e32 v72, 0, v72
	v_mul_f32_e32 v84, v84, v84
	v_mul_f32_e32 v81, v81, v81
	v_mul_f32_e32 v82, v82, v82
	v_mul_f32_e32 v83, v83, v83
	v_cvt_pk_bf16_f32 v80, v84, v80
	v_max_f32_e32 v73, 0, v73
	v_max_f32_e32 v74, 0, v74
	v_cvt_pk_bf16_f32 v81, v81, v82
	v_cvt_pk_bf16_f32 v82, v88, v85
	v_cvt_pk_bf16_f32 v83, v86, v83
	global_store_dwordx4 v[92:93], v[80:83], off offset:256
	s_nop 1
	v_max_f32_e32 v76, 0, v76
	v_mul_f32_e32 v80, v72, v72
	v_max_f32_e32 v72, 0, v77
	v_mul_f32_e32 v77, v73, v73
	v_max_f32_e32 v73, 0, v78
	v_mul_f32_e32 v78, v74, v74
	v_max_f32_e32 v74, 0, v79
	v_mul_f32_e32 v76, v76, v76
	v_mul_f32_e32 v72, v72, v72
	v_max_f32_e32 v75, 0, v75
	v_mul_f32_e32 v73, v73, v73
	v_mul_f32_e32 v74, v74, v74
	v_cvt_pk_bf16_f32 v72, v76, v72
	v_add_co_u32_e32 v76, vcc, s47, v146
	v_max_f32_e32 v64, 0, v64
	v_mul_f32_e32 v75, v75, v75
	v_cvt_pk_bf16_f32 v73, v73, v74
	v_cvt_pk_bf16_f32 v74, v80, v77
	v_addc_co_u32_e32 v77, vcc, 0, v147, vcc
	v_max_f32_e32 v65, 0, v65
	v_max_f32_e32 v66, 0, v66
	v_cvt_pk_bf16_f32 v75, v78, v75
	global_store_dwordx4 v[76:77], v[72:75], off
	s_nop 1
	v_mul_f32_e32 v72, v64, v64
	v_max_f32_e32 v64, 0, v69
	v_max_f32_e32 v68, 0, v68
	v_mul_f32_e32 v69, v65, v65
	v_max_f32_e32 v65, 0, v70
	v_mul_f32_e32 v70, v66, v66
	v_max_f32_e32 v66, 0, v71
	v_max_f32_e32 v67, 0, v67
	v_mul_f32_e32 v64, v64, v64
	v_max_f32_e32 v56, 0, v56
	v_mul_f32_e32 v68, v68, v68
	v_mul_f32_e32 v65, v65, v65
	v_mul_f32_e32 v66, v66, v66
	v_mul_f32_e32 v67, v67, v67
	v_cvt_pk_bf16_f32 v64, v68, v64
	v_max_f32_e32 v57, 0, v57
	v_max_f32_e32 v58, 0, v58
	v_cvt_pk_bf16_f32 v65, v65, v66
	v_cvt_pk_bf16_f32 v66, v72, v69
	v_cvt_pk_bf16_f32 v67, v70, v67
	global_store_dwordx4 v[76:77], v[64:67], off offset:256
	s_nop 1
	v_max_f32_e32 v60, 0, v60
	v_mul_f32_e32 v64, v56, v56
	v_max_f32_e32 v56, 0, v61
	v_mul_f32_e32 v61, v57, v57
	v_max_f32_e32 v57, 0, v62
	v_mul_f32_e32 v62, v58, v58
	v_max_f32_e32 v58, 0, v63
	v_mul_f32_e32 v60, v60, v60
	v_mul_f32_e32 v56, v56, v56
	v_max_f32_e32 v59, 0, v59
	v_mul_f32_e32 v57, v57, v57
	v_mul_f32_e32 v58, v58, v58
	v_cvt_pk_bf16_f32 v56, v60, v56
	v_add_co_u32_e32 v60, vcc, s48, v146
	v_max_f32_e32 v48, 0, v48
	v_mul_f32_e32 v59, v59, v59
	v_cvt_pk_bf16_f32 v57, v57, v58
	v_cvt_pk_bf16_f32 v58, v64, v61
	v_addc_co_u32_e32 v61, vcc, 0, v147, vcc
	v_max_f32_e32 v49, 0, v49
	v_max_f32_e32 v50, 0, v50
	v_cvt_pk_bf16_f32 v59, v62, v59
	global_store_dwordx4 v[60:61], v[56:59], off
	s_nop 1
	v_mul_f32_e32 v56, v48, v48
	v_max_f32_e32 v48, 0, v53
	v_max_f32_e32 v52, 0, v52
	v_mul_f32_e32 v53, v49, v49
	v_max_f32_e32 v49, 0, v54
	v_mul_f32_e32 v54, v50, v50
	v_max_f32_e32 v50, 0, v55
	v_max_f32_e32 v51, 0, v51
	v_mul_f32_e32 v48, v48, v48
	v_max_f32_e32 v40, 0, v40
	v_mul_f32_e32 v52, v52, v52
	v_mul_f32_e32 v49, v49, v49
	v_mul_f32_e32 v50, v50, v50
	v_mul_f32_e32 v51, v51, v51
	v_cvt_pk_bf16_f32 v48, v52, v48
	v_max_f32_e32 v41, 0, v41
	v_max_f32_e32 v42, 0, v42
	v_cvt_pk_bf16_f32 v49, v49, v50
	v_cvt_pk_bf16_f32 v50, v56, v53
	v_cvt_pk_bf16_f32 v51, v54, v51
	global_store_dwordx4 v[60:61], v[48:51], off offset:256
	s_nop 1
	v_max_f32_e32 v44, 0, v44
	v_mul_f32_e32 v48, v40, v40
	v_max_f32_e32 v40, 0, v45
	v_mul_f32_e32 v45, v41, v41
	v_max_f32_e32 v41, 0, v46
	v_mul_f32_e32 v46, v42, v42
	v_max_f32_e32 v42, 0, v47
	v_mul_f32_e32 v44, v44, v44
	v_mul_f32_e32 v40, v40, v40
	v_max_f32_e32 v43, 0, v43
	v_mul_f32_e32 v41, v41, v41
	v_mul_f32_e32 v42, v42, v42
	v_cvt_pk_bf16_f32 v40, v44, v40
	v_add_co_u32_e32 v44, vcc, s49, v146
	v_max_f32_e32 v32, 0, v32
	v_mul_f32_e32 v43, v43, v43
	v_cvt_pk_bf16_f32 v41, v41, v42
	v_cvt_pk_bf16_f32 v42, v48, v45
	v_addc_co_u32_e32 v45, vcc, 0, v147, vcc
	v_max_f32_e32 v33, 0, v33
	v_max_f32_e32 v34, 0, v34
	v_cvt_pk_bf16_f32 v43, v46, v43
	global_store_dwordx4 v[44:45], v[40:43], off
	s_nop 1
	v_mul_f32_e32 v40, v32, v32
	v_max_f32_e32 v32, 0, v37
	v_max_f32_e32 v36, 0, v36
	v_mul_f32_e32 v37, v33, v33
	v_max_f32_e32 v33, 0, v38
	v_mul_f32_e32 v38, v34, v34
	v_max_f32_e32 v34, 0, v39
	v_max_f32_e32 v35, 0, v35
	v_mul_f32_e32 v32, v32, v32
	v_max_f32_e32 v24, 0, v24
	v_mul_f32_e32 v36, v36, v36
	v_mul_f32_e32 v33, v33, v33
	v_mul_f32_e32 v34, v34, v34
	v_mul_f32_e32 v35, v35, v35
	v_cvt_pk_bf16_f32 v32, v36, v32
	v_max_f32_e32 v25, 0, v25
	v_max_f32_e32 v26, 0, v26
	v_cvt_pk_bf16_f32 v33, v33, v34
	v_cvt_pk_bf16_f32 v34, v40, v37
	v_cvt_pk_bf16_f32 v35, v38, v35
	global_store_dwordx4 v[44:45], v[32:35], off offset:256
	s_nop 1
	v_max_f32_e32 v28, 0, v28
	v_mul_f32_e32 v32, v24, v24
	v_max_f32_e32 v24, 0, v29
	v_mul_f32_e32 v29, v25, v25
	v_max_f32_e32 v25, 0, v30
	v_mul_f32_e32 v30, v26, v26
	v_max_f32_e32 v26, 0, v31
	v_mul_f32_e32 v28, v28, v28
	v_mul_f32_e32 v24, v24, v24
	v_max_f32_e32 v27, 0, v27
	v_mul_f32_e32 v25, v25, v25
	v_mul_f32_e32 v26, v26, v26
	v_cvt_pk_bf16_f32 v24, v28, v24
	v_add_co_u32_e32 v28, vcc, s50, v146
	v_max_f32_e32 v16, 0, v16
	v_mul_f32_e32 v27, v27, v27
	v_cvt_pk_bf16_f32 v25, v25, v26
	v_cvt_pk_bf16_f32 v26, v32, v29
	v_addc_co_u32_e32 v29, vcc, 0, v147, vcc
	v_max_f32_e32 v17, 0, v17
	v_max_f32_e32 v18, 0, v18
	v_cvt_pk_bf16_f32 v27, v30, v27
	global_store_dwordx4 v[28:29], v[24:27], off
	s_nop 1
	v_mul_f32_e32 v24, v16, v16
	v_max_f32_e32 v16, 0, v21
	v_max_f32_e32 v20, 0, v20
	v_mul_f32_e32 v21, v17, v17
	v_max_f32_e32 v17, 0, v22
	v_mul_f32_e32 v22, v18, v18
	v_max_f32_e32 v18, 0, v23
	v_max_f32_e32 v19, 0, v19
	v_mul_f32_e32 v16, v16, v16
	v_max_f32_e32 v8, 0, v8
	v_mul_f32_e32 v20, v20, v20
	v_mul_f32_e32 v17, v17, v17
	v_mul_f32_e32 v18, v18, v18
	v_mul_f32_e32 v19, v19, v19
	v_cvt_pk_bf16_f32 v16, v20, v16
	v_max_f32_e32 v9, 0, v9
	v_max_f32_e32 v10, 0, v10
	v_cvt_pk_bf16_f32 v17, v17, v18
	v_cvt_pk_bf16_f32 v18, v24, v21
	v_cvt_pk_bf16_f32 v19, v22, v19
	global_store_dwordx4 v[28:29], v[16:19], off offset:256
	s_nop 1
	v_max_f32_e32 v12, 0, v12
	v_mul_f32_e32 v16, v8, v8
	v_max_f32_e32 v8, 0, v13
	v_mul_f32_e32 v13, v9, v9
	v_max_f32_e32 v9, 0, v14
	v_mul_f32_e32 v14, v10, v10
	v_max_f32_e32 v10, 0, v15
	v_mul_f32_e32 v12, v12, v12
	v_mul_f32_e32 v8, v8, v8
	v_max_f32_e32 v11, 0, v11
	v_mul_f32_e32 v9, v9, v9
	v_mul_f32_e32 v10, v10, v10
	v_cvt_pk_bf16_f32 v8, v12, v8
	v_add_co_u32_e32 v12, vcc, s51, v146
	v_max_f32_e32 v0, 0, v0
	v_max_f32_e32 v1, 0, v1
	v_max_f32_e32 v2, 0, v2
	v_mul_f32_e32 v11, v11, v11
	v_cvt_pk_bf16_f32 v9, v9, v10
	v_cvt_pk_bf16_f32 v10, v16, v13
	v_addc_co_u32_e32 v13, vcc, 0, v147, vcc
	v_cvt_pk_bf16_f32 v11, v14, v11
	global_store_dwordx4 v[12:13], v[8:11], off
	v_max_f32_e32 v3, 0, v3
	v_max_f32_e32 v4, 0, v4
	v_mul_f32_e32 v8, v0, v0
	v_max_f32_e32 v0, 0, v5
	v_mul_f32_e32 v5, v1, v1
	v_max_f32_e32 v1, 0, v6
	v_mul_f32_e32 v6, v2, v2
	v_max_f32_e32 v2, 0, v7
	v_mul_f32_e32 v0, v0, v0
	v_mul_f32_e32 v1, v1, v1
	v_mul_f32_e32 v2, v2, v2
	v_mul_f32_e32 v3, v3, v3
	v_mul_f32_e32 v4, v4, v4
	v_cvt_pk_bf16_f32 v0, v4, v0
	v_cvt_pk_bf16_f32 v1, v1, v2
	v_cvt_pk_bf16_f32 v2, v8, v5
	v_cvt_pk_bf16_f32 v3, v6, v3
	global_store_dwordx4 v[12:13], v[0:3], off offset:256
	s_andn2_b64 vcc, exec, s[4:5]
	s_mov_b64 s[4:5], -1
	s_cbranch_vccnz .LBB5_5
	s_andn2_b64 vcc, exec, s[8:9]
	s_cbranch_vccnz .LBB5_4
	s_barrier
	s_branch .LBB5_4

.LBB12_12:
	s_lshl_b32 s13, s20, 8
	v_max_f32_e32 v120, 0, v120
	s_add_i32 s22, s13, s40
	v_max_f32_e32 v121, 0, v121
	v_max_f32_e32 v122, 0, v122
	s_ashr_i32 s23, s22, 31
	s_lshl_b32 s20, s21, 8
	v_mul_f32_e32 v152, v120, v120
	v_max_f32_e32 v120, 0, v125
	s_ashr_i32 s21, s20, 31
	s_lshl_b64 s[22:23], s[22:23], 13
	v_max_f32_e32 v124, 0, v124
	v_mul_f32_e32 v125, v121, v121
	v_max_f32_e32 v121, 0, v126
	v_mul_f32_e32 v126, v122, v122
	v_max_f32_e32 v122, 0, v127
	v_max_f32_e32 v123, 0, v123
	s_or_b64 s[20:21], s[20:21], s[4:5]
	v_lshl_add_u64 v[146:147], v[136:137], 0, s[22:23]
	v_mul_f32_e32 v120, v120, v120
	v_max_f32_e32 v112, 0, v112
	v_lshl_add_u64 v[146:147], s[20:21], 1, v[146:147]
	v_mul_f32_e32 v124, v124, v124
	v_mul_f32_e32 v121, v121, v121
	v_mul_f32_e32 v122, v122, v122
	v_mul_f32_e32 v123, v123, v123
	v_cvt_pk_bf16_f32 v120, v124, v120
	v_max_f32_e32 v113, 0, v113
	v_max_f32_e32 v114, 0, v114
	v_cvt_pk_bf16_f32 v121, v121, v122
	v_cvt_pk_bf16_f32 v122, v152, v125
	v_cvt_pk_bf16_f32 v123, v126, v123
	global_store_dwordx4 v[146:147], v[120:123], off
	s_nop 1
	v_mul_f32_e32 v120, v112, v112
	v_max_f32_e32 v112, 0, v117
	v_max_f32_e32 v116, 0, v116
	v_mul_f32_e32 v117, v113, v113
	v_max_f32_e32 v113, 0, v118
	v_mul_f32_e32 v118, v114, v114
	v_max_f32_e32 v114, 0, v119
	v_max_f32_e32 v115, 0, v115
	v_mul_f32_e32 v112, v112, v112
	v_max_f32_e32 v104, 0, v104
	v_mul_f32_e32 v116, v116, v116
	v_mul_f32_e32 v113, v113, v113
	v_mul_f32_e32 v114, v114, v114
	v_mul_f32_e32 v115, v115, v115
	v_cvt_pk_bf16_f32 v112, v116, v112
	v_max_f32_e32 v105, 0, v105
	v_max_f32_e32 v106, 0, v106
	v_cvt_pk_bf16_f32 v113, v113, v114
	v_cvt_pk_bf16_f32 v114, v120, v117
	v_cvt_pk_bf16_f32 v115, v118, v115
	global_store_dwordx4 v[146:147], v[112:115], off offset:256
	s_nop 1
	v_max_f32_e32 v108, 0, v108
	v_mul_f32_e32 v112, v104, v104
	v_max_f32_e32 v104, 0, v109
	v_mul_f32_e32 v109, v105, v105
	v_max_f32_e32 v105, 0, v110
	v_mul_f32_e32 v110, v106, v106
	v_max_f32_e32 v106, 0, v111
	v_mul_f32_e32 v108, v108, v108
	v_mul_f32_e32 v104, v104, v104
	v_max_f32_e32 v107, 0, v107
	v_mul_f32_e32 v105, v105, v105
	v_mul_f32_e32 v106, v106, v106
	v_cvt_pk_bf16_f32 v104, v108, v104
	v_add_co_u32_e32 v108, vcc, s46, v146
	v_max_f32_e32 v96, 0, v96
	v_mul_f32_e32 v107, v107, v107
	v_cvt_pk_bf16_f32 v105, v105, v106
	v_cvt_pk_bf16_f32 v106, v112, v109
	v_addc_co_u32_e32 v109, vcc, 0, v147, vcc
	v_max_f32_e32 v97, 0, v97
	v_max_f32_e32 v98, 0, v98
	v_cvt_pk_bf16_f32 v107, v110, v107
	global_store_dwordx4 v[108:109], v[104:107], off
	s_nop 1
	v_mul_f32_e32 v104, v96, v96
	v_max_f32_e32 v96, 0, v101
	v_max_f32_e32 v100, 0, v100
	v_mul_f32_e32 v101, v97, v97
	v_max_f32_e32 v97, 0, v102
	v_mul_f32_e32 v102, v98, v98
	v_max_f32_e32 v98, 0, v103
	v_max_f32_e32 v99, 0, v99
	v_mul_f32_e32 v96, v96, v96
	v_max_f32_e32 v88, 0, v88
	v_mul_f32_e32 v100, v100, v100
	v_mul_f32_e32 v97, v97, v97
	v_mul_f32_e32 v98, v98, v98
	v_mul_f32_e32 v99, v99, v99
	v_cvt_pk_bf16_f32 v96, v100, v96
	v_max_f32_e32 v89, 0, v89
	v_max_f32_e32 v90, 0, v90
	v_cvt_pk_bf16_f32 v97, v97, v98
	v_cvt_pk_bf16_f32 v98, v104, v101
	v_cvt_pk_bf16_f32 v99, v102, v99
	global_store_dwordx4 v[108:109], v[96:99], off offset:256
	s_nop 1
	v_max_f32_e32 v92, 0, v92
	v_mul_f32_e32 v96, v88, v88
	v_max_f32_e32 v88, 0, v93
	v_mul_f32_e32 v93, v89, v89
	v_max_f32_e32 v89, 0, v94
	v_mul_f32_e32 v94, v90, v90
	v_max_f32_e32 v90, 0, v95
	v_mul_f32_e32 v92, v92, v92
	v_mul_f32_e32 v88, v88, v88
	v_max_f32_e32 v91, 0, v91
	v_mul_f32_e32 v89, v89, v89
	v_mul_f32_e32 v90, v90, v90
	v_cvt_pk_bf16_f32 v88, v92, v88
	v_add_co_u32_e32 v92, vcc, s47, v146
	v_max_f32_e32 v80, 0, v80
	v_mul_f32_e32 v91, v91, v91
	v_cvt_pk_bf16_f32 v89, v89, v90
	v_cvt_pk_bf16_f32 v90, v96, v93
	v_addc_co_u32_e32 v93, vcc, 0, v147, vcc
	v_max_f32_e32 v81, 0, v81
	v_max_f32_e32 v82, 0, v82
	v_cvt_pk_bf16_f32 v91, v94, v91
	global_store_dwordx4 v[92:93], v[88:91], off
	s_nop 1
	v_mul_f32_e32 v88, v80, v80
	v_max_f32_e32 v80, 0, v85
	v_max_f32_e32 v84, 0, v84
	v_mul_f32_e32 v85, v81, v81
	v_max_f32_e32 v81, 0, v86
	v_mul_f32_e32 v86, v82, v82
	v_max_f32_e32 v82, 0, v87
	v_max_f32_e32 v83, 0, v83
	v_mul_f32_e32 v80, v80, v80
	v_max_f32_e32 v72, 0, v72
	v_mul_f32_e32 v84, v84, v84
	v_mul_f32_e32 v81, v81, v81
	v_mul_f32_e32 v82, v82, v82
	v_mul_f32_e32 v83, v83, v83
	v_cvt_pk_bf16_f32 v80, v84, v80
	v_max_f32_e32 v73, 0, v73
	v_max_f32_e32 v74, 0, v74
	v_cvt_pk_bf16_f32 v81, v81, v82
	v_cvt_pk_bf16_f32 v82, v88, v85
	v_cvt_pk_bf16_f32 v83, v86, v83
	global_store_dwordx4 v[92:93], v[80:83], off offset:256
	s_nop 1
	v_max_f32_e32 v76, 0, v76
	v_mul_f32_e32 v80, v72, v72
	v_max_f32_e32 v72, 0, v77
	v_mul_f32_e32 v77, v73, v73
	v_max_f32_e32 v73, 0, v78
	v_mul_f32_e32 v78, v74, v74
	v_max_f32_e32 v74, 0, v79
	v_mul_f32_e32 v76, v76, v76
	v_mul_f32_e32 v72, v72, v72
	v_max_f32_e32 v75, 0, v75
	v_mul_f32_e32 v73, v73, v73
	v_mul_f32_e32 v74, v74, v74
	v_cvt_pk_bf16_f32 v72, v76, v72
	v_add_co_u32_e32 v76, vcc, s48, v146
	v_max_f32_e32 v64, 0, v64
	v_mul_f32_e32 v75, v75, v75
	v_cvt_pk_bf16_f32 v73, v73, v74
	v_cvt_pk_bf16_f32 v74, v80, v77
	v_addc_co_u32_e32 v77, vcc, 0, v147, vcc
	v_max_f32_e32 v65, 0, v65
	v_max_f32_e32 v66, 0, v66
	v_cvt_pk_bf16_f32 v75, v78, v75
	global_store_dwordx4 v[76:77], v[72:75], off
	s_nop 1
	v_mul_f32_e32 v72, v64, v64
	v_max_f32_e32 v64, 0, v69
	v_max_f32_e32 v68, 0, v68
	v_mul_f32_e32 v69, v65, v65
	v_max_f32_e32 v65, 0, v70
	v_mul_f32_e32 v70, v66, v66
	v_max_f32_e32 v66, 0, v71
	v_max_f32_e32 v67, 0, v67
	v_mul_f32_e32 v64, v64, v64
	v_max_f32_e32 v56, 0, v56
	v_mul_f32_e32 v68, v68, v68
	v_mul_f32_e32 v65, v65, v65
	v_mul_f32_e32 v66, v66, v66
	v_mul_f32_e32 v67, v67, v67
	v_cvt_pk_bf16_f32 v64, v68, v64
	v_max_f32_e32 v57, 0, v57
	v_max_f32_e32 v58, 0, v58
	v_cvt_pk_bf16_f32 v65, v65, v66
	v_cvt_pk_bf16_f32 v66, v72, v69
	v_cvt_pk_bf16_f32 v67, v70, v67
	global_store_dwordx4 v[76:77], v[64:67], off offset:256
	s_nop 1
	v_max_f32_e32 v60, 0, v60
	v_mul_f32_e32 v64, v56, v56
	v_max_f32_e32 v56, 0, v61
	v_mul_f32_e32 v61, v57, v57
	v_max_f32_e32 v57, 0, v62
	v_mul_f32_e32 v62, v58, v58
	v_max_f32_e32 v58, 0, v63
	v_mul_f32_e32 v60, v60, v60
	v_mul_f32_e32 v56, v56, v56
	v_max_f32_e32 v59, 0, v59
	v_mul_f32_e32 v57, v57, v57
	v_mul_f32_e32 v58, v58, v58
	v_cvt_pk_bf16_f32 v56, v60, v56
	v_add_co_u32_e32 v60, vcc, s49, v146
	v_max_f32_e32 v48, 0, v48
	v_mul_f32_e32 v59, v59, v59
	v_cvt_pk_bf16_f32 v57, v57, v58
	v_cvt_pk_bf16_f32 v58, v64, v61
	v_addc_co_u32_e32 v61, vcc, 0, v147, vcc
	v_max_f32_e32 v49, 0, v49
	v_max_f32_e32 v50, 0, v50
	v_cvt_pk_bf16_f32 v59, v62, v59
	global_store_dwordx4 v[60:61], v[56:59], off
	s_nop 1
	v_mul_f32_e32 v56, v48, v48
	v_max_f32_e32 v48, 0, v53
	v_max_f32_e32 v52, 0, v52
	v_mul_f32_e32 v53, v49, v49
	v_max_f32_e32 v49, 0, v54
	v_mul_f32_e32 v54, v50, v50
	v_max_f32_e32 v50, 0, v55
	v_max_f32_e32 v51, 0, v51
	v_mul_f32_e32 v48, v48, v48
	v_max_f32_e32 v40, 0, v40
	v_mul_f32_e32 v52, v52, v52
	v_mul_f32_e32 v49, v49, v49
	v_mul_f32_e32 v50, v50, v50
	v_mul_f32_e32 v51, v51, v51
	v_cvt_pk_bf16_f32 v48, v52, v48
	v_max_f32_e32 v41, 0, v41
	v_max_f32_e32 v42, 0, v42
	v_cvt_pk_bf16_f32 v49, v49, v50
	v_cvt_pk_bf16_f32 v50, v56, v53
	v_cvt_pk_bf16_f32 v51, v54, v51
	global_store_dwordx4 v[60:61], v[48:51], off offset:256
	s_nop 1
	v_max_f32_e32 v44, 0, v44
	v_mul_f32_e32 v48, v40, v40
	v_max_f32_e32 v40, 0, v45
	v_mul_f32_e32 v45, v41, v41
	v_max_f32_e32 v41, 0, v46
	v_mul_f32_e32 v46, v42, v42
	v_max_f32_e32 v42, 0, v47
	v_mul_f32_e32 v44, v44, v44
	v_mul_f32_e32 v40, v40, v40
	v_max_f32_e32 v43, 0, v43
	v_mul_f32_e32 v41, v41, v41
	v_mul_f32_e32 v42, v42, v42
	v_cvt_pk_bf16_f32 v40, v44, v40
	v_add_co_u32_e32 v44, vcc, s50, v146
	v_max_f32_e32 v32, 0, v32
	v_mul_f32_e32 v43, v43, v43
	v_cvt_pk_bf16_f32 v41, v41, v42
	v_cvt_pk_bf16_f32 v42, v48, v45
	v_addc_co_u32_e32 v45, vcc, 0, v147, vcc
	v_max_f32_e32 v33, 0, v33
	v_max_f32_e32 v34, 0, v34
	v_cvt_pk_bf16_f32 v43, v46, v43
	global_store_dwordx4 v[44:45], v[40:43], off
	s_nop 1
	v_mul_f32_e32 v40, v32, v32
	v_max_f32_e32 v32, 0, v37
	v_max_f32_e32 v36, 0, v36
	v_mul_f32_e32 v37, v33, v33
	v_max_f32_e32 v33, 0, v38
	v_mul_f32_e32 v38, v34, v34
	v_max_f32_e32 v34, 0, v39
	v_max_f32_e32 v35, 0, v35
	v_mul_f32_e32 v32, v32, v32
	v_max_f32_e32 v24, 0, v24
	v_mul_f32_e32 v36, v36, v36
	v_mul_f32_e32 v33, v33, v33
	v_mul_f32_e32 v34, v34, v34
	v_mul_f32_e32 v35, v35, v35
	v_cvt_pk_bf16_f32 v32, v36, v32
	v_max_f32_e32 v25, 0, v25
	v_max_f32_e32 v26, 0, v26
	v_cvt_pk_bf16_f32 v33, v33, v34
	v_cvt_pk_bf16_f32 v34, v40, v37
	v_cvt_pk_bf16_f32 v35, v38, v35
	global_store_dwordx4 v[44:45], v[32:35], off offset:256
	s_nop 1
	v_max_f32_e32 v28, 0, v28
	v_mul_f32_e32 v32, v24, v24
	v_max_f32_e32 v24, 0, v29
	v_mul_f32_e32 v29, v25, v25
	v_max_f32_e32 v25, 0, v30
	v_mul_f32_e32 v30, v26, v26
	v_max_f32_e32 v26, 0, v31
	v_mul_f32_e32 v28, v28, v28
	v_mul_f32_e32 v24, v24, v24
	v_max_f32_e32 v27, 0, v27
	v_mul_f32_e32 v25, v25, v25
	v_mul_f32_e32 v26, v26, v26
	v_cvt_pk_bf16_f32 v24, v28, v24
	v_add_co_u32_e32 v28, vcc, s51, v146
	v_max_f32_e32 v16, 0, v16
	v_mul_f32_e32 v27, v27, v27
	v_cvt_pk_bf16_f32 v25, v25, v26
	v_cvt_pk_bf16_f32 v26, v32, v29
	v_addc_co_u32_e32 v29, vcc, 0, v147, vcc
	v_max_f32_e32 v17, 0, v17
	v_max_f32_e32 v18, 0, v18
	v_cvt_pk_bf16_f32 v27, v30, v27
	global_store_dwordx4 v[28:29], v[24:27], off
	s_nop 1
	v_mul_f32_e32 v24, v16, v16
	v_max_f32_e32 v16, 0, v21
	v_max_f32_e32 v20, 0, v20
	v_mul_f32_e32 v21, v17, v17
	v_max_f32_e32 v17, 0, v22
	v_mul_f32_e32 v22, v18, v18
	v_max_f32_e32 v18, 0, v23
	v_max_f32_e32 v19, 0, v19
	v_mul_f32_e32 v16, v16, v16
	v_max_f32_e32 v8, 0, v8
	v_mul_f32_e32 v20, v20, v20
	v_mul_f32_e32 v17, v17, v17
	v_mul_f32_e32 v18, v18, v18
	v_mul_f32_e32 v19, v19, v19
	v_cvt_pk_bf16_f32 v16, v20, v16
	v_max_f32_e32 v9, 0, v9
	v_max_f32_e32 v10, 0, v10
	v_cvt_pk_bf16_f32 v17, v17, v18
	v_cvt_pk_bf16_f32 v18, v24, v21
	v_cvt_pk_bf16_f32 v19, v22, v19
	global_store_dwordx4 v[28:29], v[16:19], off offset:256
	s_nop 1
	v_max_f32_e32 v12, 0, v12
	v_mul_f32_e32 v16, v8, v8
	v_max_f32_e32 v8, 0, v13
	v_mul_f32_e32 v13, v9, v9
	v_max_f32_e32 v9, 0, v14
	v_mul_f32_e32 v14, v10, v10
	v_max_f32_e32 v10, 0, v15
	v_mul_f32_e32 v12, v12, v12
	v_mul_f32_e32 v8, v8, v8
	v_max_f32_e32 v11, 0, v11
	v_mul_f32_e32 v9, v9, v9
	v_mul_f32_e32 v10, v10, v10
	v_cvt_pk_bf16_f32 v8, v12, v8
	v_add_co_u32_e32 v12, vcc, s52, v146
	v_max_f32_e32 v0, 0, v0
	v_max_f32_e32 v1, 0, v1
	v_max_f32_e32 v2, 0, v2
	v_mul_f32_e32 v11, v11, v11
	v_cvt_pk_bf16_f32 v9, v9, v10
	v_cvt_pk_bf16_f32 v10, v16, v13
	v_addc_co_u32_e32 v13, vcc, 0, v147, vcc
	v_cvt_pk_bf16_f32 v11, v14, v11
	global_store_dwordx4 v[12:13], v[8:11], off
	v_max_f32_e32 v3, 0, v3
	v_max_f32_e32 v4, 0, v4
	v_mul_f32_e32 v8, v0, v0
	v_max_f32_e32 v0, 0, v5
	v_mul_f32_e32 v5, v1, v1
	v_max_f32_e32 v1, 0, v6
	v_mul_f32_e32 v6, v2, v2
	v_max_f32_e32 v2, 0, v7
	v_mul_f32_e32 v0, v0, v0
	v_mul_f32_e32 v1, v1, v1
	v_mul_f32_e32 v2, v2, v2
	v_mul_f32_e32 v3, v3, v3
	v_mul_f32_e32 v4, v4, v4
	v_cvt_pk_bf16_f32 v0, v4, v0
	v_cvt_pk_bf16_f32 v1, v1, v2
	v_cvt_pk_bf16_f32 v2, v8, v5
	v_cvt_pk_bf16_f32 v3, v6, v3
	global_store_dwordx4 v[12:13], v[0:3], off offset:256
	s_mov_b64 s[20:21], -1
	s_mov_b64 vcc, s[0:1]
	s_cbranch_vccz .LBB12_5
	s_andn2_b64 vcc, exec, s[6:7]
	s_cbranch_vccnz .LBB12_4
	s_barrier
	s_branch .LBB12_4
